# attention stagger 1600 cycles
# baseline (speedup 1.0000x reference)
.LBB0_830:
	s_cmp_eq_u32 s29, 0
	s_cbranch_scc1 .Lattn_nostag
	s_sleep 25
